# k32 + K/V chunks v2: inside each 4 KiB chunk [64-byte column piece][16 keys], so a P4a store and a K DMA are each 1 KiB contiguous
# baseline (speedup 1.0000x reference)
.LBB0_561:
	s_mul_i32 s98, s65, 171
	s_lshr_b32 s98, s98, 11
	s_mul_i32 s99, s98, 12
	s_sub_i32 s99, s65, s99
	s_cmp_lt_u32 s99, 4
	s_cbranch_scc1 .Lkv_q
	s_and_b32 s100, s46, 15
	s_lshl_b32 s100, s100, 8
	v_add_u32_e32 v209, s100, v1
	s_sub_i32 s99, s99, 4
	s_lshr_b32 s100, s99, 2
	s_and_b32 s99, s99, 3
	s_lshl_b32 s99, s99, 9
	s_lshl_b32 s100, s100, 13
	s_add_i32 s99, s99, s100
	s_lshr_b32 s100, s46, 4
	s_lshl_b32 s100, s100, 11
	s_add_i32 s99, s99, s100
	s_mul_i32 s100, s98, 0x1800
	s_addk_i32 s100, 0x800
	v_lshrrev_b32_e32 v210, 5, v162
	v_and_b32_e32 v211, 31, v162
	v_lshlrev_b32_e32 v210, 10, v210
	v_lshl_add_u32 v210, v211, 1, v210
	v_add_u32_e32 v210, s100, v210
	v_mov_b32_e32 v211, 0
	v_lshl_add_u64 v[210:211], s[36:37], 0, v[210:211]
	s_lshl_b32 s98, s98, 1
	s_sub_i32 s100, 12, s98
	s_lshl_b32 s101, 1, s98
	s_add_i32 s101, s101, -1
	v_add_u32_e32 v206, 0, v209
	v_and_b32_e32 v207, s101, v206
	v_lshlrev_b32_e32 v207, s100, v207
	v_lshrrev_b32_e32 v208, s98, v206
	v_or_b32_e32 v207, v207, v208
	v_lshrrev_b32_e32 v208, 4, v207
	v_add_u32_e32 v208, s99, v208
	v_and_b32_e32 v207, 15, v207
	v_mad_u64_u32 v[224:225], vcc, v208, s64, v[210:211]
	v_lshlrev_b32_e32 v207, 6, v207
	v_add_co_u32_e32 v224, vcc, v224, v207
	s_nop 0
	v_addc_co_u32_e32 v225, vcc, 0, v225, vcc
	v_add_co_u32_e32 v226, vcc, 0x900000, v224
	s_nop 0
	v_addc_co_u32_e32 v227, vcc, 0, v225, vcc
	v_add_u32_e32 v206, 16, v209
	v_and_b32_e32 v207, s101, v206
	v_lshlrev_b32_e32 v207, s100, v207
	v_lshrrev_b32_e32 v208, s98, v206
	v_or_b32_e32 v207, v207, v208
	v_lshrrev_b32_e32 v208, 4, v207
	v_add_u32_e32 v208, s99, v208
	v_and_b32_e32 v207, 15, v207
	v_mad_u64_u32 v[228:229], vcc, v208, s64, v[210:211]
	v_lshlrev_b32_e32 v207, 6, v207
	v_add_co_u32_e32 v228, vcc, v228, v207
	s_nop 0
	v_addc_co_u32_e32 v229, vcc, 0, v229, vcc
	v_add_co_u32_e32 v230, vcc, 0x900000, v228
	s_nop 0
	v_addc_co_u32_e32 v231, vcc, 0, v229, vcc
	v_add_u32_e32 v206, 32, v209
	v_and_b32_e32 v207, s101, v206
	v_lshlrev_b32_e32 v207, s100, v207
	v_lshrrev_b32_e32 v208, s98, v206
	v_or_b32_e32 v207, v207, v208
	v_lshrrev_b32_e32 v208, 4, v207
	v_add_u32_e32 v208, s99, v208
	v_and_b32_e32 v207, 15, v207
	v_mad_u64_u32 v[232:233], vcc, v208, s64, v[210:211]
	v_lshlrev_b32_e32 v207, 6, v207
	v_add_co_u32_e32 v232, vcc, v232, v207
	s_nop 0
	v_addc_co_u32_e32 v233, vcc, 0, v233, vcc
	v_add_co_u32_e32 v234, vcc, 0x900000, v232
	s_nop 0
	v_addc_co_u32_e32 v235, vcc, 0, v233, vcc
	v_add_u32_e32 v206, 48, v209
	v_and_b32_e32 v207, s101, v206
	v_lshlrev_b32_e32 v207, s100, v207
	v_lshrrev_b32_e32 v208, s98, v206
	v_or_b32_e32 v207, v207, v208
	v_lshrrev_b32_e32 v208, 4, v207
	v_add_u32_e32 v208, s99, v208
	v_and_b32_e32 v207, 15, v207
	v_mad_u64_u32 v[236:237], vcc, v208, s64, v[210:211]
	v_lshlrev_b32_e32 v207, 6, v207
	v_add_co_u32_e32 v236, vcc, v236, v207
	s_nop 0
	v_addc_co_u32_e32 v237, vcc, 0, v237, vcc
	v_add_co_u32_e32 v238, vcc, 0x900000, v236
	s_nop 0
	v_addc_co_u32_e32 v239, vcc, 0, v237, vcc
	v_add_u32_e32 v206, 0x80, v209
	v_and_b32_e32 v207, s101, v206
	v_lshlrev_b32_e32 v207, s100, v207
	v_lshrrev_b32_e32 v208, s98, v206
	v_or_b32_e32 v207, v207, v208
	v_lshrrev_b32_e32 v208, 4, v207
	v_add_u32_e32 v208, s99, v208
	v_and_b32_e32 v207, 15, v207
	v_mad_u64_u32 v[240:241], vcc, v208, s64, v[210:211]
	v_lshlrev_b32_e32 v207, 6, v207
	v_add_co_u32_e32 v240, vcc, v240, v207
	s_nop 0
	v_addc_co_u32_e32 v241, vcc, 0, v241, vcc
	v_add_co_u32_e32 v242, vcc, 0x900000, v240
	s_nop 0
	v_addc_co_u32_e32 v243, vcc, 0, v241, vcc
	v_add_u32_e32 v206, 0x90, v209
	v_and_b32_e32 v207, s101, v206
	v_lshlrev_b32_e32 v207, s100, v207
	v_lshrrev_b32_e32 v208, s98, v206
	v_or_b32_e32 v207, v207, v208
	v_lshrrev_b32_e32 v208, 4, v207
	v_add_u32_e32 v208, s99, v208
	v_and_b32_e32 v207, 15, v207
	v_mad_u64_u32 v[244:245], vcc, v208, s64, v[210:211]
	v_lshlrev_b32_e32 v207, 6, v207
	v_add_co_u32_e32 v244, vcc, v244, v207
	s_nop 0
	v_addc_co_u32_e32 v245, vcc, 0, v245, vcc
	v_add_co_u32_e32 v246, vcc, 0x900000, v244
	s_nop 0
	v_addc_co_u32_e32 v247, vcc, 0, v245, vcc
	v_add_u32_e32 v206, 0xa0, v209
	v_and_b32_e32 v207, s101, v206
	v_lshlrev_b32_e32 v207, s100, v207
	v_lshrrev_b32_e32 v208, s98, v206
	v_or_b32_e32 v207, v207, v208
	v_lshrrev_b32_e32 v208, 4, v207
	v_add_u32_e32 v208, s99, v208
	v_and_b32_e32 v207, 15, v207
	v_mad_u64_u32 v[248:249], vcc, v208, s64, v[210:211]
	v_lshlrev_b32_e32 v207, 6, v207
	v_add_co_u32_e32 v248, vcc, v248, v207
	s_nop 0
	v_addc_co_u32_e32 v249, vcc, 0, v249, vcc
	v_add_co_u32_e32 v250, vcc, 0x900000, v248
	s_nop 0
	v_addc_co_u32_e32 v251, vcc, 0, v249, vcc
	v_add_u32_e32 v206, 0xb0, v209
	v_and_b32_e32 v207, s101, v206
	v_lshlrev_b32_e32 v207, s100, v207
	v_lshrrev_b32_e32 v208, s98, v206
	v_or_b32_e32 v207, v207, v208
	v_lshrrev_b32_e32 v208, 4, v207
	v_add_u32_e32 v208, s99, v208
	v_and_b32_e32 v207, 15, v207
	v_mad_u64_u32 v[252:253], vcc, v208, s64, v[210:211]
	v_lshlrev_b32_e32 v207, 6, v207
	v_add_co_u32_e32 v252, vcc, v252, v207
	s_nop 0
	v_addc_co_u32_e32 v253, vcc, 0, v253, vcc
	v_add_co_u32_e32 v254, vcc, 0x900000, v252
	s_nop 0
	v_addc_co_u32_e32 v255, vcc, 0, v253, vcc
	s_branch .Lkv_done

.LBB0_671:
	s_cmp_lt_i32 s94, 6
	s_cselect_b64 s[4:5], -1, 0
	s_add_u32 s38, s14, 0x2c600000
	s_addc_u32 s39, s15, 0
	s_add_u32 s72, s14, 0x5be00000
	s_addc_u32 s73, s15, 0
	s_and_b64 s[24:25], s[4:5], s[0:1]
	s_andn2_b64 vcc, exec, s[24:25]
	v_writelane_b32 v222, s72, 8
	s_nop 1
	v_writelane_b32 v222, s73, 9
	s_cbranch_vccnz .LBB0_1026
	v_writelane_b32 v222, s24, 10
	v_mov_b32_e32 v1, v0
	s_nop 0
	v_writelane_b32 v222, s25, 11
	v_writelane_b32 v222, s91, 12
	v_writelane_b32 v222, s96, 13
	s_nop 1
	v_writelane_b32 v222, s97, 14
	v_writelane_b32 v222, s94, 15
	s_nop 1
	v_writelane_b32 v222, s95, 16
	v_writelane_b32 v222, s92, 17
	s_nop 1
	v_writelane_b32 v222, s93, 18
	v_writelane_b32 v222, s90, 19
	s_nop 0
	v_readlane_b32 s0, v222, 2
	s_cmpk_gt_i32 s0, 0xbff
	v_readfirstlane_b32 s0, v1
	s_cbranch_scc1 .LBB0_960
	s_add_u32 s4, s14, 0x32600000
	s_addc_u32 s5, s15, 0
	s_ashr_i32 s8, s0, 6
	s_sub_i32 s1, 11, s8
	v_writelane_b32 v222, s4, 20
	s_cmp_lt_i32 s8, 4
	s_cselect_b32 s1, s8, s1
	v_writelane_b32 v222, s5, 21
	s_ashr_i32 s0, s0, 1
	v_writelane_b32 v222, s1, 22
	s_andn2_b32 s0, s0, 63
	v_bfe_u32 v2, v1, 2, 2
	v_lshl_or_b32 v3, v2, 4, s0
	s_lshl_b32 s0, s8, 3
	v_readlane_b32 s54, v222, 2
	v_and_b32_e32 v40, 15, v1
	v_bfe_u32 v41, v1, 4, 2
	v_and_or_b32 v42, s0, 8, v3
	v_lshlrev_b32_e32 v4, 2, v1
	s_ashr_i32 s0, s54, 9
	v_lshlrev_b32_e32 v118, 4, v41
	v_lshlrev_b32_e32 v3, 6, v40
	v_and_b32_e32 v4, 32, v4
	s_and_b32 s0, s0, -2
	v_bitop3_b32 v43, v118, v4, v3 bitop3:0x36
	v_lshlrev_b32_e32 v3, 4, v1
	s_sub_i32 s0, 5, s0
	v_lshl_or_b32 v125, s1, 4, v40
	v_add_u32_e32 v4, 0x2000, v3
	s_and_b32 s1, s54, 31
	s_lshl_b32 s0, -1, s0
	s_lshl_b32 s3, s8, 10
	v_ashrrev_i32_e32 v5, 31, v4
	s_andn2_b32 s0, s1, s0
	v_lshrrev_b32_e32 v5, 22, v5
	s_cmp_eq_u32 s0, 0
	v_add_u32_e32 v5, v4, v5
	s_cselect_b64 s[6:7], -1, 0
	s_ashr_i32 s4, s54, 10
	v_ashrrev_i32_e32 v5, 10, v5
	s_lshl_b32 s10, s4, 1
	v_mul_i32_i24_e32 v7, 0x400, v5
	s_sub_i32 s0, 5, s10
	v_sub_u32_e32 v4, v4, v7
	s_lshl_b32 s5, -1, s0
	s_lshl_b32 s9, s54, 4
	v_lshrrev_b32_e32 v7, 4, v4
	s_andn2_b32 s11, s1, s5
	s_lshr_b32 s5, s1, s0
	s_and_b32 s9, s9, 0x3000
	v_bitop3_b32 v4, v7, v4, 32 bitop3:0x6c
	s_or_b32 s5, s5, s9
	v_ashrrev_i32_e32 v7, 31, v4
	s_lshl_b64 s[0:1], 0x4800, s10
	s_mul_i32 s5, s5, 0x9000
	v_lshrrev_b32_e32 v7, 26, v7
	s_add_u32 s9, s36, s5
	s_mulk_i32 s4, 0xc00
	v_add_u32_e32 v7, v4, v7
	s_addc_u32 s16, s37, 0
	s_ashr_i32 s5, s4, 31
	v_ashrrev_i32_e32 v8, 6, v7
	v_and_b32_e32 v7, 0xc0, v7
	s_lshl_b64 s[4:5], s[4:5], 1
	v_lshlrev_b32_e32 v6, 5, v5
	v_sub_u32_e32 v4, v4, v7
	v_mov_b32_e32 v10, 1
	s_add_u32 s4, s9, s4
	v_and_b32_e32 v6, 32, v6
	v_ashrrev_i16_sdwa v4, v10, sext(v4) dst_sel:DWORD dst_unused:UNUSED_PAD src0_sel:DWORD src1_sel:BYTE_0
	s_addc_u32 s5, s16, s5
	s_and_b32 s9, s66, 0x700
	v_add_u32_sdwa v122, v6, sext(v4) dst_sel:DWORD dst_unused:UNUSED_PAD src0_sel:DWORD src1_sel:WORD_0
	v_lshlrev_b32_e32 v4, 3, v5
	s_add_u32 s4, s4, s9
	v_and_b32_e32 v4, -16, v4
	s_addc_u32 s5, s5, 0
	v_add_u32_e32 v124, v8, v4
	v_ashrrev_i32_e32 v4, 31, v1
	s_cmp_lg_u64 s[6:7], 0
	v_lshlrev_b32_e32 v120, 2, v41
	v_lshrrev_b32_e32 v4, 26, v4
	v_cndmask_b32_e64 v13, 0, 1, s[6:7]
	s_addc_u32 s6, s11, 0
	v_and_or_b32 v44, v1, 3, v120
	v_add_u32_e32 v4, v1, v4
	v_bfe_i32 v1, v1, 27, 1
	s_lshl_b32 s6, s6, 7
	v_lshrrev_b32_e32 v1, 22, v1
	s_add_i32 s9, s6, 0xffffff80
	v_lshlrev_b32_e32 v2, 2, v2
	v_add_u32_e32 v1, v3, v1
	s_ashr_i32 s6, s9, 31
	v_lshl_or_b32 v129, s8, 4, v2
	v_ashrrev_i32_e32 v11, 6, v4
	v_and_b32_e32 v1, 0xfffffc00, v1
	s_mul_i32 s6, s0, s6
	s_mul_hi_u32 s7, s0, s9
	v_add_u32_e32 v2, s9, v129
	v_lshlrev_b32_e32 v4, 5, v11
	v_sub_u32_e32 v1, v3, v1
	s_add_i32 s6, s7, s6
	s_mul_i32 s7, s1, s9
	v_ashrrev_i32_e32 v3, 31, v2
	v_and_b32_e32 v12, 32, v4
	s_add_i32 s7, s6, s7
	s_mul_i32 s6, s0, s9
	v_mul_lo_u32 v4, s0, v3
	v_mul_lo_u32 v5, s1, v2
	v_mad_u64_u32 v[2:3], s[8:9], s0, v2, 0
	v_add3_u32 v3, v3, v4, v5
	v_lshl_add_u64 v[4:5], v[2:3], 1, s[4:5]
	v_mov_b32_e32 v2, 0
	v_lshlrev_b32_e32 v6, 4, v44
	v_mov_b32_e32 v7, v2
	v_lshl_add_u64 v[4:5], v[4:5], 0, v[6:7]
	s_mov_b64 s[8:9], 0x1000
	s_lshl_b64 s[6:7], s[6:7], 1
	v_lshl_add_u64 v[6:7], v[4:5], 0, s[8:9]
	s_movk_i32 s8, 0x1000
	s_add_u32 s6, s4, s6
	v_add_co_u32_e32 v4, vcc, s8, v4
	s_addc_u32 s7, s5, s7
	s_nop 0
	v_addc_co_u32_e32 v5, vcc, 0, v5, vcc
	s_lshl_b64 s[8:9], 0x9000, s10
	v_lshl_add_u64 v[8:9], s[0:1], 1, v[6:7]
	s_lshr_b32 s98, s54, 10
	s_lshl_b32 s99, s98, 1
	s_sub_i32 s100, 5, s99
	s_and_b32 s101, s54, 31
	s_lshr_b32 s98, s101, s100
	s_sub_i32 s99, 8, s99
	s_lshl_b32 s98, s98, s99
	s_lshl_b32 s99, -1, s100
	s_andn2_b32 s101, s101, s99
	s_cmp_eq_u32 s101, 0
	s_cselect_b32 s99, 8, 0
	s_lshl_b32 s101, s101, 3
	s_add_i32 s98, s98, s101
	s_add_i32 s98, s98, s99
	s_add_i32 s98, s98, -8
	s_bfe_u32 s101, s54, 0x20008
	s_lshl_b32 s101, s101, 11
	s_add_i32 s98, s98, s101
	s_bfe_u32 s101, s54, 0x30005
	s_lshl_b32 s101, s101, 8
	s_add_i32 s98, s98, s101
	s_mul_i32 s98, s98, 0x9000
	s_lshr_b32 s101, s54, 10
	s_mul_i32 s101, s101, 0x1800
	s_add_i32 s98, s98, s101
	s_add_u32 s98, s36, s98
	s_addc_u32 s99, s37, 0
	v_lshrrev_b32_e32 v240, 4, v129
	v_and_b32_e32 v241, 15, v129
	v_mul_u32_u24_e32 v240, 0x9000, v240
	v_lshl_add_u32 v240, v241, 6, v240
	v_lshrrev_b32_e32 v241, 2, v44
	v_lshl_add_u32 v240, v241, 10, v240
	v_and_b32_e32 v241, 3, v44
	v_lshl_add_u32 v240, v241, 4, v240
	v_add_u32_e32 v240, 0x12000800, v240
	v_mov_b32_e32 v241, 0
	v_lshl_add_u64 v[4:5], s[98:99], 0, v[240:241]
	global_load_dwordx4 v[22:25], v[4:5], off
	v_lshrrev_b32_e32 v240, 4, v129
	v_and_b32_e32 v241, 15, v129
	v_mul_u32_u24_e32 v240, 0x9000, v240
	v_lshl_add_u32 v240, v241, 6, v240
	v_lshrrev_b32_e32 v241, 2, v44
	v_lshl_add_u32 v240, v241, 10, v240
	v_and_b32_e32 v241, 3, v44
	v_lshl_add_u32 v240, v241, 4, v240
	v_add_u32_e32 v240, 0x12000840, v240
	v_mov_b32_e32 v241, 0
	v_lshl_add_u64 v[8:9], s[98:99], 0, v[240:241]
	global_load_dwordx4 v[26:29], v[8:9], off
	v_lshl_add_u64 v[4:5], s[8:9], 1, v[6:7]
	v_lshrrev_b32_e32 v240, 4, v129
	v_and_b32_e32 v241, 15, v129
	v_mul_u32_u24_e32 v240, 0x9000, v240
	v_lshl_add_u32 v240, v241, 6, v240
	v_lshrrev_b32_e32 v241, 2, v44
	v_lshl_add_u32 v240, v241, 10, v240
	v_and_b32_e32 v241, 3, v44
	v_lshl_add_u32 v240, v241, 4, v240
	v_add_u32_e32 v240, 0x12000880, v240
	v_mov_b32_e32 v241, 0
	v_lshl_add_u64 v[4:5], s[98:99], 0, v[240:241]
	global_load_dwordx4 v[30:33], v[4:5], off
	v_mad_u64_u32 v[4:5], s[8:9], s0, 6, v[6:7]
	v_mov_b32_e32 v6, v5
	v_mad_u64_u32 v[6:7], s[8:9], s1, 6, v[6:7]
	v_mov_b32_e32 v5, v6
	v_lshrrev_b32_e32 v240, 4, v129
	v_and_b32_e32 v241, 15, v129
	v_mul_u32_u24_e32 v240, 0x9000, v240
	v_lshl_add_u32 v240, v241, 6, v240
	v_lshrrev_b32_e32 v241, 2, v44
	v_lshl_add_u32 v240, v241, 10, v240
	v_and_b32_e32 v241, 3, v44
	v_lshl_add_u32 v240, v241, 4, v240
	v_add_u32_e32 v240, 0x120008c0, v240
	v_mov_b32_e32 v241, 0
	v_lshl_add_u64 v[4:5], s[98:99], 0, v[240:241]
	global_load_dwordx4 v[34:37], v[4:5], off
	v_lshrrev_b32_e32 v3, 4, v1
	v_bitop3_b32 v1, v3, v1, 32 bitop3:0x6c
	v_ashrrev_i32_e32 v3, 31, v1
	v_lshrrev_b32_e32 v3, 26, v3
	v_add_u32_e32 v3, v1, v3
	v_ashrrev_i32_e32 v4, 6, v3
	v_and_b32_e32 v3, 0xc0, v3
	v_sub_u32_e32 v1, v1, v3
	v_ashrrev_i16_sdwa v1, v10, sext(v1) dst_sel:DWORD dst_unused:UNUSED_PAD src0_sel:DWORD src1_sel:BYTE_0
	v_add_u32_sdwa v126, v12, sext(v1) dst_sel:DWORD dst_unused:UNUSED_PAD src0_sel:DWORD src1_sel:WORD_0
	v_lshlrev_b32_e32 v1, 3, v11
	v_and_b32_e32 v1, -16, v1
	v_add_u32_e32 v128, v4, v1
	v_ashrrev_i32_e32 v1, 31, v128
	v_mul_lo_u32 v3, s0, v1
	v_mul_lo_u32 v6, s1, v128
	v_mad_u64_u32 v[4:5], s[8:9], s0, v128, 0
	v_add3_u32 v5, v5, v3, v6
	v_lshl_add_u64 v[4:5], v[4:5], 1, s[6:7]
	v_ashrrev_i32_e32 v127, 31, v126
	v_lshl_add_u64 v[4:5], v[126:127], 1, v[4:5]
	s_mov_b64 s[16:17], 0x800
	s_add_i32 s3, s3, 0
	v_lshl_add_u64 v[6:7], v[4:5], 0, s[16:17]
	s_mov_b32 m0, s3
	v_ashrrev_i32_e32 v121, 31, v124
	v_lshrrev_b32_e32 v240, 4, v128
	v_and_b32_e32 v241, 15, v128
	v_mul_u32_u24_e32 v240, 0x9000, v240
	v_lshl_add_u32 v240, v241, 6, v240
	v_lshrrev_b32_e32 v241, 5, v126
	v_lshl_add_u32 v240, v241, 10, v240
	v_and_b32_e32 v241, 31, v126
	v_lshl_add_u32 v240, v241, 1, v240
	v_add_u32_e32 v240, 0x800, v240
	v_mov_b32_e32 v241, 0
	v_lshl_add_u64 v[6:7], s[98:99], 0, v[240:241]
	global_load_lds_dwordx4 v[6:7], off
	v_mul_lo_u32 v3, s0, v121
	v_mul_lo_u32 v8, s1, v124
	v_mad_u64_u32 v[6:7], s[8:9], s0, v124, 0
	v_add3_u32 v7, v7, v3, v8
	v_lshl_add_u64 v[6:7], v[6:7], 1, s[6:7]
	v_ashrrev_i32_e32 v123, 31, v122
	v_lshl_add_u64 v[6:7], v[122:123], 1, v[6:7]
	s_add_i32 s6, s3, 0x2000
	v_lshl_add_u64 v[8:9], v[6:7], 0, s[16:17]
	v_writelane_b32 v222, s6, 23
	s_mov_b32 m0, s6
	s_mov_b64 s[60:61], 0x880
	s_add_i32 s6, s3, 0x4000
	v_lshrrev_b32_e32 v240, 4, v124
	v_and_b32_e32 v241, 15, v124
	v_mul_u32_u24_e32 v240, 0x9000, v240
	v_lshl_add_u32 v240, v241, 6, v240
	v_lshrrev_b32_e32 v241, 5, v122
	v_lshl_add_u32 v240, v241, 10, v240
	v_and_b32_e32 v241, 31, v122
	v_lshl_add_u32 v240, v241, 1, v240
	v_add_u32_e32 v240, 0x800, v240
	v_mov_b32_e32 v241, 0
	v_lshl_add_u64 v[8:9], s[98:99], 0, v[240:241]
	global_load_lds_dwordx4 v[8:9], off
	v_lshl_add_u64 v[4:5], v[4:5], 0, s[60:61]
	v_writelane_b32 v222, s6, 24
	s_mov_b32 m0, s6
	s_add_i32 s6, s3, 0x6000
	v_lshrrev_b32_e32 v240, 4, v128
	v_and_b32_e32 v241, 15, v128
	v_mul_u32_u24_e32 v240, 0x9000, v240
	v_lshl_add_u32 v240, v241, 6, v240
	v_lshrrev_b32_e32 v241, 5, v126
	v_lshl_add_u32 v240, v241, 10, v240
	v_and_b32_e32 v241, 31, v126
	v_lshl_add_u32 v240, v241, 1, v240
	v_add_u32_e32 v240, 0x1000, v240
	v_mov_b32_e32 v241, 0
	v_lshl_add_u64 v[4:5], s[98:99], 0, v[240:241]
	global_load_lds_dwordx4 v[4:5], off
	v_lshl_add_u64 v[4:5], v[6:7], 0, s[60:61]
	s_mov_b32 m0, s6
	v_lshl_add_u32 v3, s11, 7, v125
	v_lshrrev_b32_e32 v240, 4, v124
	v_and_b32_e32 v241, 15, v124
	v_mul_u32_u24_e32 v240, 0x9000, v240
	v_lshl_add_u32 v240, v241, 6, v240
	v_lshrrev_b32_e32 v241, 5, v122
	v_lshl_add_u32 v240, v241, 10, v240
	v_and_b32_e32 v241, 31, v122
	v_lshl_add_u32 v240, v241, 1, v240
	v_add_u32_e32 v240, 0x1000, v240
	v_mov_b32_e32 v241, 0
	v_lshl_add_u64 v[4:5], s[98:99], 0, v[240:241]
	global_load_lds_dwordx4 v[4:5], off
	v_ashrrev_i32_e32 v4, 31, v3
	v_mul_lo_u32 v6, s0, v4
	v_mul_lo_u32 v7, s1, v3
	v_mad_u64_u32 v[4:5], s[0:1], s0, v3, 0
	v_add3_u32 v5, v5, v6, v7
	v_lshl_add_u64 v[4:5], v[4:5], 1, s[4:5]
	v_mov_b32_e32 v119, v2
	v_lshl_add_u64 v[4:5], v[4:5], 0, v[118:119]
	v_readfirstlane_b32 s25, v13
	global_load_dwordx4 v[14:17], v[4:5], off
	global_load_dwordx4 v[10:13], v[4:5], off offset:64
	global_load_dwordx4 v[18:21], v[4:5], off offset:128
	global_load_dwordx4 v[6:9], v[4:5], off offset:192
	s_movk_i32 s0, 0x880
	v_mad_u32_u24 v3, v44, s0, 0
	s_waitcnt vmcnt(0)
	v_and_b32_e32 v4, 0xffff, v22
	v_lshrrev_b32_e32 v22, 16, v22
	s_mov_b32 s24, 0xffff0000
	v_add_u32_e32 v3, v3, v42
	v_and_b32_e32 v5, 0xffff, v30
	v_and_or_b32 v38, v26, s24, v22
	v_lshrrev_b32_e32 v22, 16, v30
	v_lshl_or_b32 v4, v26, 16, v4
	v_add_u32_e32 v119, 0x8000, v3
	v_and_b32_e32 v3, 0xffff, v23
	v_lshl_or_b32 v5, v34, 16, v5
	v_and_or_b32 v39, v34, s24, v22
	ds_write2_b64 v119, v[4:5], v[38:39] offset1:34
	v_lshl_or_b32 v4, v27, 16, v3
	v_and_b32_e32 v3, 0xffff, v31
	v_lshl_or_b32 v5, v35, 16, v3
	v_lshrrev_b32_e32 v3, 16, v23
	v_and_or_b32 v22, v27, s24, v3
	v_lshrrev_b32_e32 v3, 16, v31
	v_and_or_b32 v23, v35, s24, v3
	v_and_b32_e32 v3, 0xffff, v24
	ds_write2_b64 v119, v[4:5], v[22:23] offset0:68 offset1:102
	v_lshl_or_b32 v4, v28, 16, v3
	v_and_b32_e32 v3, 0xffff, v32
	v_lshl_or_b32 v5, v36, 16, v3
	v_lshrrev_b32_e32 v3, 16, v24
	v_and_or_b32 v22, v28, s24, v3
	v_lshrrev_b32_e32 v3, 16, v32
	v_and_or_b32 v23, v36, s24, v3
	v_and_b32_e32 v3, 0xffff, v25
	ds_write2_b64 v119, v[4:5], v[22:23] offset0:136 offset1:170
	v_lshl_or_b32 v4, v29, 16, v3
	v_and_b32_e32 v3, 0xffff, v33
	v_lshl_or_b32 v5, v37, 16, v3
	v_lshrrev_b32_e32 v3, 16, v25
	v_and_or_b32 v22, v29, s24, v3
	v_lshrrev_b32_e32 v3, 16, v33
	v_and_or_b32 v23, v37, s24, v3
	ds_write2_b64 v119, v[4:5], v[22:23] offset0:204 offset1:238
	v_or_b32_e32 v4, 0x60, v40
	v_sub_u32_e32 v136, v4, v120
	v_or_b32_e32 v4, 0x50, v40
	v_sub_u32_e32 v137, v4, v120
	v_or_b32_e32 v4, 64, v40
	v_sub_u32_e32 v138, v4, v120
	v_or_b32_e32 v4, 48, v40
	v_sub_u32_e32 v139, v4, v120
	v_or_b32_e32 v4, 32, v40
	v_sub_u32_e32 v140, v4, v120
	v_or_b32_e32 v4, 16, v40
	v_sub_u32_e32 v141, v4, v120
	v_or_b32_e32 v4, 0xf0, v40
	v_sub_u32_e32 v143, v4, v120
	v_or_b32_e32 v4, 0xe0, v40
	v_sub_u32_e32 v144, v4, v120
	v_or_b32_e32 v4, 0xd0, v40
	v_sub_u32_e32 v145, v4, v120
	v_or_b32_e32 v4, 0xc0, v40
	v_sub_u32_e32 v147, v4, v120
	v_or_b32_e32 v4, 0xb0, v40
	v_writelane_b32 v222, s6, 25
	v_sub_u32_e32 v148, v4, v120
	v_or_b32_e32 v4, 0xa0, v40
	v_cmp_eq_u32_e64 s[4:5], 0, v41
	v_sub_u32_e32 v149, v4, v120
	v_or_b32_e32 v4, 0x90, v40
	v_writelane_b32 v222, s4, 26
	v_sub_u32_e32 v150, v4, v120
	v_or_b32_e32 v4, 0x80, v40
	v_writelane_b32 v222, s5, 27
	s_add_i32 s4, 0, 0x18800
	v_sub_u32_e32 v151, v4, v120
	v_mov_b32_e32 v4, s4
	v_or_b32_e32 v3, 0x70, v40
	v_mad_u32_u24 v4, v44, s0, v4
	s_add_i32 s0, 0, 0x10800
	v_sub_u32_e32 v133, v3, v120
	v_mul_u32_u24_e32 v3, 0x110, v40
	v_add_u32_e32 v152, s0, v43
	s_add_i32 s0, 0, 0x18840
	s_movk_i32 s1, 0x110
	v_add3_u32 v135, 0, v3, v118
	v_add3_u32 v153, s4, v3, v118
	v_mov_b32_e32 v3, s0
	s_add_i32 s0, 0, 0x18880
	v_mad_u32_u24 v154, v40, s1, v3
	v_mov_b32_e32 v3, s0
	s_add_i32 s0, 0, 0x188c0
	v_mad_u32_u24 v155, v40, s1, v3
	v_mov_b32_e32 v3, s0
	v_mad_u32_u24 v156, v40, s1, v3
	s_mov_b32 s1, 0x42800000
	v_writelane_b32 v222, s0, 28
	s_waitcnt vmcnt(0) expcnt(0) lgkmcnt(0)
	s_barrier
	v_writelane_b32 v222, s1, 29
	s_mov_b32 s1, 2.0
	v_writelane_b32 v222, s0, 30
	s_mov_b32 s56, 0x3e0293ee
	v_mbcnt_lo_u32_b32 v3, -1, 0
	v_writelane_b32 v222, s1, 31
	s_mov_b32 s1, 0x40400000
	s_mov_b32 s49, 0
	v_lshlrev_b32_e32 v130, 3, v44
	v_lshlrev_b32_e32 v132, 3, v41
	v_add_u32_e32 v131, 0, v43
	v_sub_u32_e32 v134, v120, v40
	v_sub_u32_e32 v142, v40, v120
	v_mov_b32_e32 v157, 0xf149f2ca
	s_mov_b32 s57, 0x3fb8aa3b
	v_writelane_b32 v222, s0, 32
	s_mov_b32 s63, 0x41800000
	s_mov_b32 s65, 0x41880000
	s_mov_b32 s67, 0x41900000
	s_mov_b32 s69, 0x41980000
	s_mov_b32 s71, 0x42000000
	s_mov_b32 s73, 0x42040000
	s_mov_b32 s75, 0x42080000
	s_mov_b32 s77, 0x420c0000
	s_mov_b32 s79, 0x42400000
	s_mov_b32 s81, 0x42440000
	s_mov_b32 s83, 0x42480000
	s_mov_b32 s85, 0x424c0000
	s_mov_b32 s87, 0x42820000
	s_mov_b32 s89, 0x42840000
	s_mov_b32 s91, 0x42860000
	s_mov_b32 s93, 0x42a00000
	s_mov_b32 s95, 0x42a20000
	s_mov_b32 s97, 0x42a40000
	s_mov_b32 s21, 0x42a60000
	s_mov_b32 s11, 0x42c00000
	s_mov_b32 s43, 0x42c20000
	s_mov_b32 s19, 0x42c40000
	s_mov_b32 s47, 0x42c60000
	s_mov_b32 s45, 0x42e00000
	s_mov_b32 s17, 0x42e20000
	s_mov_b32 s51, 0x42e40000
	s_mov_b32 s53, 0x42e60000
	v_add_u32_e32 v158, v4, v42
	v_mov_b32_e32 v159, 0x42800000
	v_mbcnt_hi_u32_b32 v160, -1, v3
	v_mov_b32_e32 v162, 0xf149f2ca
	v_mov_b32_e32 v164, 0
	v_mov_b32_e32 v58, 0
	v_mov_b32_e32 v59, v2
	v_mov_b32_e32 v60, v2
	v_mov_b32_e32 v61, v2
	v_mov_b32_e32 v54, 0
	v_mov_b32_e32 v55, v2
	v_mov_b32_e32 v56, v2
	v_mov_b32_e32 v57, v2
	v_mov_b32_e32 v62, 0
	v_mov_b32_e32 v63, v2
	v_mov_b32_e32 v64, v2
	v_mov_b32_e32 v65, v2
	v_mov_b32_e32 v66, 0
	v_mov_b32_e32 v67, v2
	v_mov_b32_e32 v68, v2
	v_mov_b32_e32 v69, v2
	v_mov_b32_e32 v70, 0
	v_mov_b32_e32 v71, v2
	v_mov_b32_e32 v72, v2
	v_mov_b32_e32 v73, v2
	v_mov_b32_e32 v74, 0
	v_mov_b32_e32 v75, v2
	v_mov_b32_e32 v76, v2
	v_mov_b32_e32 v77, v2
	v_mov_b32_e32 v78, 0
	v_mov_b32_e32 v79, v2
	v_mov_b32_e32 v80, v2
	v_mov_b32_e32 v81, v2
	v_mov_b32_e32 v82, 0
	v_mov_b32_e32 v83, v2
	v_mov_b32_e32 v84, v2
	v_mov_b32_e32 v85, v2
	v_writelane_b32 v222, s1, 33
	s_branch .LBB0_675

.LBB0_678:
	s_cmpk_lt_i32 s55, 0xc00
	v_mov_b32_e32 v86, 0
	s_cselect_b64 s[4:5], -1, 0
	s_cmpk_gt_i32 s55, 0xbff
	v_mov_b32_e32 v87, 0
	v_mov_b32_e32 v88, 0
	v_mov_b32_e32 v89, 0
	v_mov_b32_e32 v90, 0
	v_mov_b32_e32 v91, 0
	v_mov_b32_e32 v92, 0
	v_mov_b32_e32 v93, 0
	v_mov_b32_e32 v94, 0
	v_mov_b32_e32 v95, 0
	v_mov_b32_e32 v96, 0
	v_mov_b32_e32 v97, 0
	v_mov_b32_e32 v98, 0
	v_mov_b32_e32 v99, 0
	v_mov_b32_e32 v100, 0
	v_mov_b32_e32 v101, 0
	s_cbranch_scc1 .LBB0_680
	s_lshr_b32 s98, s55, 10
	s_lshl_b32 s99, s98, 1
	s_sub_i32 s100, 5, s99
	s_and_b32 s101, s55, 31
	s_lshr_b32 s98, s101, s100
	s_sub_i32 s99, 8, s99
	s_lshl_b32 s98, s98, s99
	s_lshl_b32 s99, -1, s100
	s_andn2_b32 s101, s101, s99
	s_lshl_b32 s99, s40, 3
	s_lshl_b32 s101, s101, 3
	s_add_i32 s98, s98, s101
	s_add_i32 s98, s98, s99
	s_add_i32 s98, s98, -8
	s_bfe_u32 s101, s55, 0x20008
	s_lshl_b32 s101, s101, 11
	s_add_i32 s98, s98, s101
	s_bfe_u32 s101, s55, 0x30005
	s_lshl_b32 s101, s101, 8
	s_add_i32 s98, s98, s101
	s_mul_i32 s98, s98, 0x9000
	s_lshr_b32 s101, s55, 10
	s_mul_i32 s101, s101, 0x1800
	s_add_i32 s98, s98, s101
	s_add_u32 s98, s36, s98
	s_addc_u32 s99, s37, 0
	s_ashr_i32 s6, s55, 10
	s_lshl_b32 s10, s6, 1
	s_sub_i32 s1, 5, s10
	s_and_b32 s0, s55, 31
	s_lshl_b32 s7, -1, s1
	s_lshl_b32 s9, s55, 4
	s_andn2_b32 s8, s0, s7
	s_lshr_b32 s7, s0, s1
	s_and_b32 s9, s9, 0x3000
	s_or_b32 s7, s7, s9
	s_lshl_b64 s[0:1], 0x4800, s10
	s_mul_i32 s7, s7, 0x9000
	s_add_u32 s9, s36, s7
	s_mulk_i32 s6, 0xc00
	s_addc_u32 s16, s37, 0
	s_ashr_i32 s7, s6, 31
	s_lshl_b64 s[6:7], s[6:7], 1
	s_add_u32 s6, s9, s6
	s_addc_u32 s7, s16, s7
	s_lshl_b32 s9, s55, 3
	s_and_b32 s9, s9, 0x700
	s_add_u32 s6, s6, s9
	s_addc_u32 s7, s7, 0
	s_lshl_b32 s9, s40, 7
	s_lshl_b32 s8, s8, 7
	s_xor_b32 s9, s9, 0x80
	s_sub_i32 s16, s8, s9
	s_ashr_i32 s8, s16, 31
	s_mul_i32 s8, s0, s8
	s_mul_hi_u32 s9, s0, s16
	s_add_i32 s8, s9, s8
	s_mul_i32 s9, s1, s16
	s_add_i32 s9, s8, s9
	s_mul_i32 s8, s0, s16
	s_lshl_b64 s[8:9], s[8:9], 1
	s_add_u32 s8, s6, s8
	v_mul_lo_u32 v3, s1, v128
	v_mul_lo_u32 v22, s0, v1
	v_mad_u64_u32 v[4:5], vcc, s0, v128, 0
	s_addc_u32 s9, s7, s9
	v_add3_u32 v5, v5, v22, v3
	v_lshl_add_u64 v[4:5], v[4:5], 1, s[8:9]
	v_lshl_add_u64 v[4:5], v[126:127], 1, v[4:5]
	s_mov_b64 s[58:59], 0x800
	v_lshl_add_u64 v[22:23], v[4:5], 0, s[58:59]
	s_add_i32 m0, s3, 0x10800
	v_mul_lo_u32 v3, s1, v124
	v_lshrrev_b32_e32 v240, 4, v128
	v_and_b32_e32 v241, 15, v128
	v_mul_u32_u24_e32 v240, 0x9000, v240
	v_lshl_add_u32 v240, v241, 6, v240
	v_lshrrev_b32_e32 v241, 5, v126
	v_lshl_add_u32 v240, v241, 10, v240
	v_and_b32_e32 v241, 31, v126
	v_lshl_add_u32 v240, v241, 1, v240
	v_add_u32_e32 v240, 0x800, v240
	v_mov_b32_e32 v241, 0
	v_lshl_add_u64 v[22:23], s[98:99], 0, v[240:241]
	global_load_lds_dwordx4 v[22:23], off
	v_mul_lo_u32 v24, s0, v121
	v_mad_u64_u32 v[22:23], vcc, s0, v124, 0
	v_add3_u32 v23, v23, v24, v3
	v_lshl_add_u64 v[22:23], v[22:23], 1, s[8:9]
	v_lshl_add_u64 v[22:23], v[122:123], 1, v[22:23]
	v_lshl_add_u64 v[24:25], v[22:23], 0, s[58:59]
	s_add_i32 m0, s3, 0x12800
	v_lshl_add_u64 v[4:5], v[4:5], 0, s[60:61]
	v_lshrrev_b32_e32 v240, 4, v124
	v_and_b32_e32 v241, 15, v124
	v_mul_u32_u24_e32 v240, 0x9000, v240
	v_lshl_add_u32 v240, v241, 6, v240
	v_lshrrev_b32_e32 v241, 5, v122
	v_lshl_add_u32 v240, v241, 10, v240
	v_and_b32_e32 v241, 31, v122
	v_lshl_add_u32 v240, v241, 1, v240
	v_add_u32_e32 v240, 0x800, v240
	v_mov_b32_e32 v241, 0
	v_lshl_add_u64 v[24:25], s[98:99], 0, v[240:241]
	global_load_lds_dwordx4 v[24:25], off
	s_add_i32 m0, s3, 0x14800
	v_add_u32_e32 v3, s16, v129
	v_lshrrev_b32_e32 v240, 4, v128
	v_and_b32_e32 v241, 15, v128
	v_mul_u32_u24_e32 v240, 0x9000, v240
	v_lshl_add_u32 v240, v241, 6, v240
	v_lshrrev_b32_e32 v241, 5, v126
	v_lshl_add_u32 v240, v241, 10, v240
	v_and_b32_e32 v241, 31, v126
	v_lshl_add_u32 v240, v241, 1, v240
	v_add_u32_e32 v240, 0x1000, v240
	v_mov_b32_e32 v241, 0
	v_lshl_add_u64 v[4:5], s[98:99], 0, v[240:241]
	global_load_lds_dwordx4 v[4:5], off
	v_lshl_add_u64 v[4:5], v[22:23], 0, s[60:61]
	s_add_i32 m0, s3, 0x16800
	v_mul_lo_u32 v23, s1, v3
	v_lshrrev_b32_e32 v240, 4, v124
	v_and_b32_e32 v241, 15, v124
	v_mul_u32_u24_e32 v240, 0x9000, v240
	v_lshl_add_u32 v240, v241, 6, v240
	v_lshrrev_b32_e32 v241, 5, v122
	v_lshl_add_u32 v240, v241, 10, v240
	v_and_b32_e32 v241, 31, v122
	v_lshl_add_u32 v240, v241, 1, v240
	v_add_u32_e32 v240, 0x1000, v240
	v_mov_b32_e32 v241, 0
	v_lshl_add_u64 v[4:5], s[98:99], 0, v[240:241]
	global_load_lds_dwordx4 v[4:5], off
	v_ashrrev_i32_e32 v4, 31, v3
	v_mul_lo_u32 v22, s0, v4
	v_mad_u64_u32 v[4:5], s[8:9], s0, v3, 0
	v_add3_u32 v5, v5, v22, v23
	v_lshl_add_u64 v[4:5], v[4:5], 1, s[6:7]
	v_lshlrev_b32_e32 v22, 1, v130
	v_mov_b32_e32 v23, v2
	v_lshl_add_u64 v[4:5], v[4:5], 0, v[22:23]
	s_mov_b64 s[6:7], 0x1000
	v_lshl_add_u64 v[22:23], v[4:5], 0, s[6:7]
	s_movk_i32 s6, 0x1000
	v_add_co_u32_e32 v4, vcc, s6, v4
	s_lshl_b64 s[6:7], 0x9000, s10
	s_nop 0
	v_addc_co_u32_e32 v5, vcc, 0, v5, vcc
	v_lshl_add_u64 v[24:25], s[0:1], 1, v[22:23]
	v_lshrrev_b32_e32 v240, 4, v129
	v_and_b32_e32 v241, 15, v129
	v_mul_u32_u24_e32 v240, 0x9000, v240
	v_lshl_add_u32 v240, v241, 6, v240
	v_lshrrev_b32_e32 v241, 5, v130
	v_lshl_add_u32 v240, v241, 10, v240
	v_and_b32_e32 v241, 24, v130
	v_lshl_add_u32 v240, v241, 1, v240
	v_add_u32_e32 v240, 0x12000800, v240
	v_mov_b32_e32 v241, 0
	v_lshl_add_u64 v[4:5], s[98:99], 0, v[240:241]
	global_load_dwordx4 v[86:89], v[4:5], off
	v_lshrrev_b32_e32 v240, 4, v129
	v_and_b32_e32 v241, 15, v129
	v_mul_u32_u24_e32 v240, 0x9000, v240
	v_lshl_add_u32 v240, v241, 6, v240
	v_lshrrev_b32_e32 v241, 5, v130
	v_lshl_add_u32 v240, v241, 10, v240
	v_and_b32_e32 v241, 24, v130
	v_lshl_add_u32 v240, v241, 1, v240
	v_add_u32_e32 v240, 0x12000840, v240
	v_mov_b32_e32 v241, 0
	v_lshl_add_u64 v[24:25], s[98:99], 0, v[240:241]
	global_load_dwordx4 v[90:93], v[24:25], off
	v_lshl_add_u64 v[4:5], s[6:7], 1, v[22:23]
	v_mad_u64_u32 v[22:23], s[6:7], s0, 6, v[22:23]
	v_mov_b32_e32 v24, v23
	v_mad_u64_u32 v[24:25], s[0:1], s1, 6, v[24:25]
	v_mov_b32_e32 v23, v24
	v_lshrrev_b32_e32 v240, 4, v129
	v_and_b32_e32 v241, 15, v129
	v_mul_u32_u24_e32 v240, 0x9000, v240
	v_lshl_add_u32 v240, v241, 6, v240
	v_lshrrev_b32_e32 v241, 5, v130
	v_lshl_add_u32 v240, v241, 10, v240
	v_and_b32_e32 v241, 24, v130
	v_lshl_add_u32 v240, v241, 1, v240
	v_add_u32_e32 v240, 0x12000880, v240
	v_mov_b32_e32 v241, 0
	v_lshl_add_u64 v[4:5], s[98:99], 0, v[240:241]
	global_load_dwordx4 v[94:97], v[4:5], off
	v_lshrrev_b32_e32 v240, 4, v129
	v_and_b32_e32 v241, 15, v129
	v_mul_u32_u24_e32 v240, 0x9000, v240
	v_lshl_add_u32 v240, v241, 6, v240
	v_lshrrev_b32_e32 v241, 5, v130
	v_lshl_add_u32 v240, v241, 10, v240
	v_and_b32_e32 v241, 24, v130
	v_lshl_add_u32 v240, v241, 1, v240
	v_add_u32_e32 v240, 0x120008c0, v240
	v_mov_b32_e32 v241, 0
	v_lshl_add_u64 v[22:23], s[98:99], 0, v[240:241]
	global_load_dwordx4 v[98:101], v[22:23], off

.LBB0_821:
	s_cmpk_lt_i32 s54, 0xc00
	s_cselect_b64 s[4:5], -1, 0
	s_cmpk_gt_i32 s54, 0xbff
	s_cselect_b64 s[8:9], -1, 0
	v_mov_b32_e32 v86, 0
	s_and_b64 vcc, exec, s[8:9]
	v_mov_b32_e32 v87, 0
	v_mov_b32_e32 v88, 0
	v_mov_b32_e32 v89, 0
	v_mov_b32_e32 v90, 0
	v_mov_b32_e32 v91, 0
	v_mov_b32_e32 v92, 0
	v_mov_b32_e32 v93, 0
	v_mov_b32_e32 v94, 0
	v_mov_b32_e32 v95, 0
	v_mov_b32_e32 v96, 0
	v_mov_b32_e32 v97, 0
	v_mov_b32_e32 v98, 0
	v_mov_b32_e32 v99, 0
	v_mov_b32_e32 v100, 0
	v_mov_b32_e32 v101, 0
	s_cbranch_vccnz .LBB0_823
	s_lshr_b32 s98, s54, 10
	s_lshl_b32 s99, s98, 1
	s_sub_i32 s100, 5, s99
	s_and_b32 s101, s54, 31
	s_lshr_b32 s98, s101, s100
	s_sub_i32 s99, 8, s99
	s_lshl_b32 s98, s98, s99
	s_lshl_b32 s99, -1, s100
	s_andn2_b32 s101, s101, s99
	s_lshl_b32 s99, s25, 3
	s_lshl_b32 s101, s101, 3
	s_add_i32 s98, s98, s101
	s_add_i32 s98, s98, s99
	s_add_i32 s98, s98, -8
	s_bfe_u32 s101, s54, 0x20008
	s_lshl_b32 s101, s101, 11
	s_add_i32 s98, s98, s101
	s_bfe_u32 s101, s54, 0x30005
	s_lshl_b32 s101, s101, 8
	s_add_i32 s98, s98, s101
	s_mul_i32 s98, s98, 0x9000
	s_lshr_b32 s101, s54, 10
	s_mul_i32 s101, s101, 0x1800
	s_add_i32 s98, s98, s101
	s_add_u32 s98, s36, s98
	s_addc_u32 s99, s37, 0
	s_ashr_i32 s6, s54, 10
	s_lshl_b32 s10, s6, 1
	s_sub_i32 s1, 5, s10
	s_and_b32 s0, s54, 31
	s_lshl_b32 s7, -1, s1
	s_lshl_b32 s18, s54, 4
	s_andn2_b32 s16, s0, s7
	s_lshr_b32 s7, s0, s1
	s_and_b32 s18, s18, 0x3000
	s_or_b32 s7, s7, s18
	s_lshl_b64 s[0:1], 0x4800, s10
	s_mul_i32 s7, s7, 0x9000
	s_add_u32 s18, s36, s7
	s_mulk_i32 s6, 0xc00
	s_addc_u32 s20, s37, 0
	s_ashr_i32 s7, s6, 31
	s_lshl_b64 s[6:7], s[6:7], 1
	s_add_u32 s6, s18, s6
	s_addc_u32 s7, s20, s7
	s_lshl_b32 s18, s54, 3
	s_and_b32 s18, s18, 0x700
	s_add_u32 s6, s6, s18
	s_addc_u32 s7, s7, 0
	s_add_i32 s16, s16, s25
	s_lshl_b32 s16, s16, 7
	s_addk_i32 s16, 0xff80
	s_ashr_i32 s18, s16, 31
	s_mul_i32 s18, s0, s18
	s_mul_hi_u32 s20, s0, s16
	s_add_i32 s18, s20, s18
	s_mul_i32 s20, s1, s16
	s_add_i32 vcc_hi, s18, s20
	s_mul_i32 vcc_lo, s0, s16
	s_lshl_b64 vcc, vcc, 1
	s_add_u32 vcc_lo, s6, vcc_lo
	v_mul_lo_u32 v3, s1, v128
	v_mul_lo_u32 v54, s0, v1
	v_mad_u64_u32 v[4:5], s[58:59], s0, v128, 0
	s_addc_u32 vcc_hi, s7, vcc_hi
	v_add3_u32 v5, v5, v54, v3
	v_lshl_add_u64 v[4:5], v[4:5], 1, vcc
	v_lshl_add_u64 v[4:5], v[126:127], 1, v[4:5]
	s_mov_b64 s[60:61], 0x800
	s_mov_b32 m0, s3
	v_lshl_add_u64 v[54:55], v[4:5], 0, s[60:61]
	v_lshrrev_b32_e32 v240, 4, v128
	v_and_b32_e32 v241, 15, v128
	v_mul_u32_u24_e32 v240, 0x9000, v240
	v_lshl_add_u32 v240, v241, 6, v240
	v_lshrrev_b32_e32 v241, 5, v126
	v_lshl_add_u32 v240, v241, 10, v240
	v_and_b32_e32 v241, 31, v126
	v_lshl_add_u32 v240, v241, 1, v240
	v_add_u32_e32 v240, 0x800, v240
	v_mov_b32_e32 v241, 0
	v_lshl_add_u64 v[54:55], s[98:99], 0, v[240:241]
	global_load_lds_dwordx4 v[54:55], off
	v_mul_lo_u32 v3, s1, v124
	v_mul_lo_u32 v56, s0, v121
	v_mad_u64_u32 v[54:55], s[58:59], s0, v124, 0
	v_add3_u32 v55, v55, v56, v3
	v_lshl_add_u64 v[54:55], v[54:55], 1, vcc
	v_lshl_add_u64 v[54:55], v[122:123], 1, v[54:55]
	v_readlane_b32 s18, v222, 23
	v_lshl_add_u64 v[56:57], v[54:55], 0, s[60:61]
	s_mov_b64 s[60:61], 0x880
	s_mov_b32 m0, s18
	v_readlane_b32 s18, v222, 24
	v_lshrrev_b32_e32 v240, 4, v124
	v_and_b32_e32 v241, 15, v124
	v_mul_u32_u24_e32 v240, 0x9000, v240
	v_lshl_add_u32 v240, v241, 6, v240
	v_lshrrev_b32_e32 v241, 5, v122
	v_lshl_add_u32 v240, v241, 10, v240
	v_and_b32_e32 v241, 31, v122
	v_lshl_add_u32 v240, v241, 1, v240
	v_add_u32_e32 v240, 0x800, v240
	v_mov_b32_e32 v241, 0
	v_lshl_add_u64 v[56:57], s[98:99], 0, v[240:241]
	global_load_lds_dwordx4 v[56:57], off
	v_lshl_add_u64 v[4:5], v[4:5], 0, s[60:61]
	s_mov_b32 m0, s18
	v_readlane_b32 s18, v222, 25
	v_lshrrev_b32_e32 v240, 4, v128
	v_and_b32_e32 v241, 15, v128
	v_mul_u32_u24_e32 v240, 0x9000, v240
	v_lshl_add_u32 v240, v241, 6, v240
	v_lshrrev_b32_e32 v241, 5, v126
	v_lshl_add_u32 v240, v241, 10, v240
	v_and_b32_e32 v241, 31, v126
	v_lshl_add_u32 v240, v241, 1, v240
	v_add_u32_e32 v240, 0x1000, v240
	v_mov_b32_e32 v241, 0
	v_lshl_add_u64 v[4:5], s[98:99], 0, v[240:241]
	global_load_lds_dwordx4 v[4:5], off
	v_lshl_add_u64 v[4:5], v[54:55], 0, s[60:61]
	s_mov_b32 m0, s18
	v_add_u32_e32 v3, s16, v129
	v_lshrrev_b32_e32 v240, 4, v124
	v_and_b32_e32 v241, 15, v124
	v_mul_u32_u24_e32 v240, 0x9000, v240
	v_lshl_add_u32 v240, v241, 6, v240
	v_lshrrev_b32_e32 v241, 5, v122
	v_lshl_add_u32 v240, v241, 10, v240
	v_and_b32_e32 v241, 31, v122
	v_lshl_add_u32 v240, v241, 1, v240
	v_add_u32_e32 v240, 0x1000, v240
	v_mov_b32_e32 v241, 0
	v_lshl_add_u64 v[4:5], s[98:99], 0, v[240:241]
	global_load_lds_dwordx4 v[4:5], off
	v_ashrrev_i32_e32 v4, 31, v3
	v_mul_lo_u32 v54, s0, v4
	v_mul_lo_u32 v55, s1, v3
	v_mad_u64_u32 v[4:5], s[58:59], s0, v3, 0
	v_add3_u32 v5, v5, v54, v55
	v_lshl_add_u64 v[4:5], v[4:5], 1, s[6:7]
	v_lshlrev_b32_e32 v54, 1, v130
	v_mov_b32_e32 v55, v2
	s_movk_i32 s16, 0x1000
	v_lshl_add_u64 v[4:5], v[4:5], 0, v[54:55]
	s_mov_b64 s[6:7], 0x1000
	v_lshl_add_u64 v[54:55], v[4:5], 0, s[6:7]
	v_add_co_u32_e32 v4, vcc, s16, v4
	s_lshl_b64 s[6:7], 0x9000, s10
	s_nop 0
	v_addc_co_u32_e32 v5, vcc, 0, v5, vcc
	v_lshl_add_u64 v[56:57], s[0:1], 1, v[54:55]
	v_lshrrev_b32_e32 v240, 4, v129
	v_and_b32_e32 v241, 15, v129
	v_mul_u32_u24_e32 v240, 0x9000, v240
	v_lshl_add_u32 v240, v241, 6, v240
	v_lshrrev_b32_e32 v241, 5, v130
	v_lshl_add_u32 v240, v241, 10, v240
	v_and_b32_e32 v241, 24, v130
	v_lshl_add_u32 v240, v241, 1, v240
	v_add_u32_e32 v240, 0x12000800, v240
	v_mov_b32_e32 v241, 0
	v_lshl_add_u64 v[4:5], s[98:99], 0, v[240:241]
	global_load_dwordx4 v[86:89], v[4:5], off
	v_lshrrev_b32_e32 v240, 4, v129
	v_and_b32_e32 v241, 15, v129
	v_mul_u32_u24_e32 v240, 0x9000, v240
	v_lshl_add_u32 v240, v241, 6, v240
	v_lshrrev_b32_e32 v241, 5, v130
	v_lshl_add_u32 v240, v241, 10, v240
	v_and_b32_e32 v241, 24, v130
	v_lshl_add_u32 v240, v241, 1, v240
	v_add_u32_e32 v240, 0x12000840, v240
	v_mov_b32_e32 v241, 0
	v_lshl_add_u64 v[56:57], s[98:99], 0, v[240:241]
	global_load_dwordx4 v[90:93], v[56:57], off
	v_lshl_add_u64 v[4:5], s[6:7], 1, v[54:55]
	v_mad_u64_u32 v[54:55], s[6:7], s0, 6, v[54:55]
	v_mov_b32_e32 v56, v55
	v_mad_u64_u32 v[56:57], s[0:1], s1, 6, v[56:57]
	v_mov_b32_e32 v55, v56
	v_lshrrev_b32_e32 v240, 4, v129
	v_and_b32_e32 v241, 15, v129
	v_mul_u32_u24_e32 v240, 0x9000, v240
	v_lshl_add_u32 v240, v241, 6, v240
	v_lshrrev_b32_e32 v241, 5, v130
	v_lshl_add_u32 v240, v241, 10, v240
	v_and_b32_e32 v241, 24, v130
	v_lshl_add_u32 v240, v241, 1, v240
	v_add_u32_e32 v240, 0x12000880, v240
	v_mov_b32_e32 v241, 0
	v_lshl_add_u64 v[4:5], s[98:99], 0, v[240:241]
	global_load_dwordx4 v[94:97], v[4:5], off
	v_lshrrev_b32_e32 v240, 4, v129
	v_and_b32_e32 v241, 15, v129
	v_mul_u32_u24_e32 v240, 0x9000, v240
	v_lshl_add_u32 v240, v241, 6, v240
	v_lshrrev_b32_e32 v241, 5, v130
	v_lshl_add_u32 v240, v241, 10, v240
	v_and_b32_e32 v241, 24, v130
	v_lshl_add_u32 v240, v241, 1, v240
	v_add_u32_e32 v240, 0x120008c0, v240
	v_mov_b32_e32 v241, 0
	v_lshl_add_u64 v[54:55], s[98:99], 0, v[240:241]
	global_load_dwordx4 v[98:101], v[54:55], off
